# P6: half of the workgroups (blockIdx bit 4) run the independent in-projection-B GEMM before G3 and the other half after, so G3's HBM streaming overlaps GEMM compute
# speedup vs baseline: 1.0028x; 1.0028x over previous
; #define G3_LOAD(O0, O1, G0, G1_, m) do { O0 = *(const v4u*)(OG + (size_t)(m) * D + 16 * F.lane); O1 = *(const v4u*)(OG + (size_t)(m) * D + 16 * F.lane + 8); \
;             G0 = *(const v4u*)(GR + (size_t)(m) * D + 16 * F.lane); G1_ = *(const v4u*)(GR + (size_t)(m) * D + 16 * F.lane + 8); } while (0)
; template <int K> __device__ __forceinline__ void run_phase(const Args& args, LAS unsigned char* ldsp) {
;     ...
;     F.G = gridDim.x; { const int bx = blockIdx.x; F.vcu = (F.G % 8 == 0) ? (bx % 8) * (F.G / 8) + bx / 8 : bx; }
;     F.out = args.out; F.ws = args.ws;
;     unsigned char* ws = args.ws;
;     const int gw = F.vcu * NWAVES + F.wave, NGW = F.G * NWAVES;
;     ...
;         const int ms = MP + gw; const bool hasS = ms < M;
;         v4u so0, so1, sg0, sg1;
;         if (hasS) G3_LOAD(so0, so1, sg0, sg1, ms);
.LBB0_1812:
	s_or_b64 exec, exec, s[4:5]
	s_bfe_u32 s99, s2, 0x10004
	s_load_dword s0, s[90:91], 0xbc
	s_waitcnt lgkmcnt(0)
	s_barrier
	s_cmp_lt_i32 s0, 7
	s_cbranch_scc1 .LBB0_2017
.Lp6_g3entry:
	s_waitcnt vmcnt(16)
	v_mov_b32_e32 v1, v0
	s_load_dword s8, s[90:91], 0xc0
	v_readfirstlane_b32 s3, v1
	s_mov_b32 s9, s2
	s_waitcnt lgkmcnt(0)
	s_and_b32 s0, s8, 7
	s_cmp_lg_u32 s0, 0
	s_cbranch_scc1 .LBB0_1815
	s_ashr_i32 s1, s2, 31
	s_lshr_b32 s1, s1, 29
	s_add_i32 s1, s2, s1
	s_and_b32 s4, s1, -8
	s_ashr_i32 s0, s8, 3
	s_sub_i32 s4, s2, s4
	s_mul_i32 s0, s0, s4
	s_ashr_i32 s1, s1, 3
	s_add_i32 s9, s0, s1
.LBB0_1815:
	s_ashr_i32 s64, s3, 6
	s_lshl_b32 s10, s9, 3
	s_add_i32 s10, s10, s64
	s_add_u32 s0, s96, 0xbd40000
	s_addc_u32 s1, s97, 0
	s_add_i32 s4, s10, 0x8000
	v_and_b32_e32 v166, 63, v1
	s_cmp_eq_u32 s99, 1
	s_cbranch_scc1 .LBB0_1825
	s_cmpk_lt_i32 s10, 0x100
	s_cselect_b64 s[6:7], -1, 0
	s_cmpk_gt_i32 s10, 0xff
	v_lshlrev_b32_e32 v38, 5, v166
	s_cbranch_scc1 .LBB0_1817
	s_ashr_i32 s5, s4, 31
	s_lshl_b64 s[12:13], s[4:5], 11
	s_add_u32 s14, s96, s12
	s_addc_u32 s15, s97, s13
	v_mov_b32_e32 v39, 0
	s_waitcnt vmcnt(0)
	v_lshl_add_u64 v[2:3], s[14:15], 0, v[38:39]
	s_add_u32 s12, s0, s12
	v_add_co_u32_e32 v20, vcc, 0x17ec0000, v2
	s_mov_b64 s[14:15], 0x17ec0000
	s_addc_u32 s13, s1, s13
	v_addc_co_u32_e32 v21, vcc, 0, v3, vcc
	v_lshl_add_u64 v[18:19], v[2:3], 0, s[14:15]
	global_load_dwordx4 v[14:17], v38, s[12:13] offset:16
	global_load_dwordx4 v[10:13], v38, s[12:13]
	global_load_dwordx4 v[2:5], v[20:21], off
	global_load_dwordx4 v[6:9], v[18:19], off offset:16

; #define LAS __attribute__((address_space(3)))
; #define SG_UNITS(u, NU) const int sg_half = F.G >> 1, sg_nf = (NU) < sg_half ? (NU) : sg_half; \
;     for (int u = (part == 0 ? ((F.vcu & 1) ? (F.vcu >> 1) : (NU)) : ((F.vcu & 1) ? (NU) : sg_nf + (F.vcu >> 1))); u < (part == 0 ? sg_nf : (NU)); u += sg_half)
; __device__ __forceinline__ void sg_gates(const Args& a, Frame& F, int part) {
;     const int fr = F.lane & 15, fq = F.lane >> 4, wr4 = F.wave >> 1, wc2 = F.wave & 1;
;     unsigned char* ws = a.ws;
;     const bf16* XB = (const bf16*)(ws + WS_XB); const bf16* Wt = (const bf16*)(ws + WS_WBT); const float* ssqs = (const float*)(ws + WS_SSQAS);
;     bf16* R = (bf16*)(ws + WS_T0); bf16* SS = (bf16*)(ws + WS_T7);
;     LAS f32x4* xch = (LAS f32x4*)F.lds;
;     SG_UNITS(u, 4 * (D / 16)) {
;         const int rq = u & 3, nb = u >> 2, n0 = 16 * nb, grow = 256 * (n0 >> 7) + (n0 & 127);
;         const unsigned t0 = sg_touch(Wt + (size_t)(grow + ((F.tid >> 4) & 15) + (F.tid >> 8) * 128) * D + (F.tid & 15) * 64);
;         const bf16* p0[2]; const bf16* p1[2];
;         { const int Rr = SG_ROW(0), ko = SG_KOFF(Rr); p0[0] = XB + (size_t)(MP + rq * 64 + Rr) * D + ko; p1[0] = p0[0]; }
;         { const int Rr = SG_ROW(1), ko = SG_KOFF(Rr), b = (Rr - 64) & 31; p0[1] = Wt + (size_t)(grow + (b >> 4) * 128 + (b & 15)) * D + ko; p1[1] = p0[1]; }
;         SgSsq q; float rs = 0.f;
;         if (wc2 == 0) sg_ssq_ld(q, ssqs, rq * 64 + wr4 * 16 + fr, fq);
;         f32x4 c[1][1] = {{{0.f, 0.f, 0.f, 0.f}}}, cs[1][1];
;         sgemm<1, 1>(c, cs, F.lds, F.wave, F.lane, p0, p1, D / 64, 1 << 30, [&] { if (wc2 == 0) rs = sg_ssq_rstd(q); });
.LBB0_1825:
	s_cmp_eq_u32 s99, 2
	s_cbranch_scc1 .Lp6_done
	s_add_u32 s14, s96, 0x3c40000
	s_addc_u32 s15, s97, 0
	s_add_u32 s10, s96, 0x7cc0000
	s_addc_u32 s11, s97, 0
	s_add_u32 s12, s96, 0x13e40000
	s_addc_u32 s13, s97, 0
	s_ashr_i32 s0, s8, 1
	s_min_i32 s1, s0, 0x100
	s_and_b32 s6, s9, 1
	s_bitcmp1_b32 s9, 0
	s_cselect_b64 s[16:17], -1, 0
	s_cmp_eq_u32 s6, 0
	s_cselect_b64 s[6:7], -1, 0
	s_ashr_i32 s65, s9, 1
	s_cmp_ge_i32 s65, s1
	s_cselect_b64 s[20:21], -1, 0
	s_or_b64 s[6:7], s[6:7], s[20:21]
	s_mov_b64 s[4:5], 0x3c40000
	s_mov_b32 s19, 0
	s_and_b64 vcc, exec, s[6:7]
	v_bfe_u32 v172, v1, 4, 4
	v_bfe_u32 v169, v1, 1, 3
	v_and_b32_e32 v168, 15, v1
	v_and_b32_e32 v176, 48, v1
	v_lshrrev_b32_e32 v175, 2, v1
	v_ashrrev_i32_e32 v173, 1, v1
	v_lshlrev_b32_e32 v174, 7, v1
	v_lshrrev_b32_e32 v167, 3, v166
	v_lshrrev_b32_e32 v170, 4, v166
	v_lshrrev_b32_e32 v171, 1, v1
	s_barrier
	s_cbranch_vccnz .LBB0_1848
	s_lshr_b32 s18, s3, 6
	s_add_u32 s22, s96, 0x1a80000
	s_addc_u32 s23, s97, 0
	s_ashr_i32 s9, s3, 7
	s_and_b32 s20, s3, 64
	s_cmp_eq_u32 s20, 0
	s_cselect_b64 s[26:27], -1, 0
	s_cmp_lg_u32 s20, 0
	s_cselect_b64 s[20:21], -1, 0
	v_lshl_or_b32 v40, s9, 4, v168
	s_lshl_b32 s9, s9, 10
	s_add_i32 s28, s9, 0
	s_movk_i32 s9, 0xff80
	v_lshlrev_b32_e32 v22, 2, v176
	v_mov_b32_e32 v23, 0
	v_and_or_b32 v41, v173, s9, v172
	s_lshl_b32 s9, s64, 3
	s_waitcnt vmcnt(0)
	v_lshl_add_u64 v[2:3], s[96:97], 0, v[22:23]
	s_mov_b64 s[24:25], 0x3b1c000
	v_or_b32_e32 v42, s9, v167
	v_lshl_add_u64 v[24:25], v[2:3], 0, s[24:25]
	v_lshrrev_b32_e32 v3, 1, v42
	v_xor_b32_e32 v4, v3, v1
	v_and_b32_e32 v22, 0x780, v174
	v_lshlrev_b32_e32 v4, 4, v4
	s_and_b32 s30, s3, 0x80
	s_and_b32 s29, s9, 0x1fffff0
	s_lshl_b32 s9, s64, 4
	v_lshl_add_u64 v[26:27], s[22:23], 0, v[22:23]
	v_and_b32_e32 v22, 0x70, v4
	s_cmp_lt_i32 s64, 4
	v_bitop3_b32 v3, v3, 7, v1 bitop3:0x48
	v_and_b32_e32 v2, 12, v175
	v_lshl_add_u64 v[28:29], s[14:15], 0, v[22:23]
	v_lshl_add_u64 v[30:31], s[22:23], 0, v[22:23]
	v_bitop3_b32 v4, v171, v170, 7 bitop3:0x6c
	v_bitop3_b32 v5, v170, v169, 4 bitop3:0x36
	s_cselect_b64 s[22:23], -1, 0
	s_cmp_gt_i32 s64, 3
	v_lshlrev_b32_e32 v22, 4, v3
	v_lshl_or_b32 v3, s18, 3, v167
	s_mov_b64 s[6:7], 0x1a80000
	v_and_or_b32 v6, s9, 16, v168
	s_cselect_b64 s[24:25], -1, 0
	s_lshl_b32 s9, s64, 10
	v_or_b32_e32 v7, s29, v168
	v_lshlrev_b32_e32 v45, 4, v4
	v_lshlrev_b32_e32 v46, 4, v5
	v_lshl_add_u64 v[4:5], s[96:97], 0, v[22:23]
	v_and_or_b32 v50, v3, 15, s30
	v_cndmask_b32_e64 v3, 0, 1, s[26:27]
	v_lshlrev_b32_e32 v22, 1, v2
	v_mbcnt_lo_u32_b32 v2, -1, 0
	v_and_or_b32 v43, v42, 15, s30
	s_add_i32 s9, s9, 0
	v_lshlrev_b32_e32 v44, 7, v7
	v_lshlrev_b32_e32 v47, 7, v6
	v_lshl_add_u32 v48, v166, 4, s28
	v_lshl_add_u64 v[32:33], v[4:5], 0, s[4:5]
	v_add_u32_e32 v49, 0x8000, v42
	s_lshl_b32 s28, s65, 6
	s_lshl_b32 s29, s0, 6
	v_lshl_add_u64 v[34:35], v[4:5], 0, s[6:7]
	s_lshl_b32 s30, s65, 3
	s_lshl_b32 s31, s0, 3
	s_lshl_b32 s33, s65, 2
	s_lshl_b32 s34, s0, 2
	v_cmp_ne_u32_e64 s[4:5], 1, v3
	v_mov_b32_e32 v51, 0x358637bd
	v_mbcnt_hi_u32_b32 v52, -1, v2
	s_mov_b32 s35, s65
	s_branch .LBB0_1828

; #define S xcd_barrier(bar);
; template <int K> __device__ __forceinline__ void run_phase(const Args& args, LAS unsigned char* ldsp) {
;     ...
;         __syncthreads();
;         sg_gates(args, F, 0);
;         pg8::Gemm g{XB, XB, (const bf16*)(ws + WS_WBT), D, D, D, 1}; pg8::StaticOrder S; S.init(MP / 256, NBP / 256, 1, F.G, (int)blockIdx.x);
;         pg8::EpiProjB E{(bf16*)(ws + WS_T0), (bf16*)(ws + WS_T7), (const float*)(ws + WS_SSQA)};
;         pg8::gemm_phase<pg8::EpiProjB, true, true>(F.lds, g, S, E);
;         sg_gates(args, F, 1);
;     }
.LBB0_2017:
	s_cmp_eq_u32 s99, 1
	s_cbranch_scc0 .Lp6_done
	s_mov_b32 s99, 2
	s_branch .Lp6_g3entry
